# v27 + grid-barrier poll de-serialisation: the 16 arrival counters are loaded back to back and summed after one wait
# speedup vs baseline: 1.0033x; 1.0033x over previous
.LBB0_788:
	s_mov_b64 s[10:11], -1
	s_mov_b64 s[16:17], -1
	s_waitcnt lgkmcnt(0)
	v_readlane_b32 s4, v252, 5
	v_readlane_b32 s5, v252, 6
	s_nop 4
	global_load_dword v0, v1, s[4:5] sc1
	v_readlane_b32 s4, v252, 7
	v_readlane_b32 s5, v252, 8
	s_nop 4
	global_load_dword v2, v1, s[4:5] sc1
	v_readlane_b32 s4, v252, 9
	v_readlane_b32 s5, v252, 10
	s_nop 4
	global_load_dword v3, v1, s[4:5] sc1
	v_readlane_b32 s4, v252, 11
	v_readlane_b32 s5, v252, 12
	s_nop 4
	global_load_dword v4, v1, s[4:5] sc1
	v_readlane_b32 s4, v252, 13
	v_readlane_b32 s5, v252, 14
	s_nop 4
	global_load_dword v5, v1, s[4:5] sc1
	v_readlane_b32 s4, v252, 15
	v_readlane_b32 s5, v252, 16
	s_nop 4
	global_load_dword v6, v1, s[4:5] sc1
	v_readlane_b32 s4, v252, 17
	v_readlane_b32 s5, v252, 18
	s_nop 4
	global_load_dword v7, v1, s[4:5] sc1
	v_readlane_b32 s4, v252, 19
	v_readlane_b32 s5, v252, 20
	s_nop 4
	global_load_dword v8, v1, s[4:5] sc1
	v_readlane_b32 s4, v252, 21
	v_readlane_b32 s5, v252, 22
	s_nop 4
	global_load_dword v9, v1, s[4:5] sc1
	v_readlane_b32 s4, v252, 23
	v_readlane_b32 s5, v252, 24
	s_nop 4
	global_load_dword v10, v1, s[4:5] sc1
	v_readlane_b32 s4, v252, 25
	v_readlane_b32 s5, v252, 26
	s_nop 4
	global_load_dword v11, v1, s[4:5] sc1
	v_readlane_b32 s4, v252, 27
	v_readlane_b32 s5, v252, 28
	s_nop 4
	global_load_dword v12, v1, s[4:5] sc1
	v_readlane_b32 s4, v252, 29
	v_readlane_b32 s5, v252, 30
	s_nop 4
	global_load_dword v13, v1, s[4:5] sc1
	v_readlane_b32 s4, v252, 31
	v_readlane_b32 s5, v252, 32
	s_nop 4
	global_load_dword v14, v1, s[4:5] sc1
	v_readlane_b32 s4, v252, 33
	v_readlane_b32 s5, v252, 34
	s_nop 4
	global_load_dword v15, v1, s[4:5] sc1
	v_readlane_b32 s4, v252, 35
	v_readlane_b32 s5, v252, 36
	s_nop 4
	global_load_dword v16, v1, s[4:5] sc1
	v_readlane_b32 s4, v253, 39
	s_waitcnt vmcnt(0)
	v_add_u32_e32 v17, v2, v0
	v_add_u32_e32 v17, v17, v3
	v_add_u32_e32 v17, v17, v4
	v_add_u32_e32 v17, v17, v5
	v_add_u32_e32 v17, v17, v6
	v_add_u32_e32 v17, v17, v7
	v_add_u32_e32 v17, v17, v8
	v_add_u32_e32 v17, v17, v9
	v_add_u32_e32 v17, v17, v10
	v_add_u32_e32 v17, v17, v11
	v_add_u32_e32 v17, v17, v12
	v_add_u32_e32 v17, v17, v13
	v_add_u32_e32 v17, v17, v14
	v_add_u32_e32 v17, v17, v15
	v_add_u32_e32 v17, v17, v16
	v_cmp_eq_u32_e32 vcc, s4, v17
	s_cbranch_vccnz .LBB0_787
	s_and_b32 s4, s1, 0xff
	s_cmp_eq_u32 s4, 0
	s_mov_b64 s[28:29], -1
	s_sleep 1
	s_cbranch_scc0 .LBB0_792
	v_readlane_b32 s4, v252, 3
	v_readlane_b32 s5, v252, 4
	s_nop 4
	global_load_dword v17, v1, s[4:5] sc1
	s_waitcnt vmcnt(0)
	v_cmp_eq_u32_e32 vcc, 0, v17
	s_cbranch_vccnz .LBB0_794
	s_mov_b64 s[28:29], 0
